# GEMM K-loop: loop-control scalar updates moved ahead of the closing barrier (back-edge rotation, tail only); otherwise v136
# baseline (speedup 1.0000x reference)
.LBB0_223:
	s_add_i32 s10, s8, 2
	s_add_u32 s11, s6, 0x80
	s_addc_u32 s9, s7, 0
	s_add_i32 s17, 0, 0x10000
	s_cmp_eq_u32 s45, s8
	s_cselect_b32 s9, s73, s9
	s_cselect_b32 s8, s72, s11
	s_cselect_b32 s19, s5, s16
	s_cselect_b32 s18, s4, s15
	s_add_i32 s11, 0, 0x14000
	v_add_u32_e32 v156, s17, v191
	v_add_u32_e32 v172, s11, v191
	ds_read_b128 v[144:147], v156
	ds_read_b128 v[148:151], v156 offset:1024
	ds_read_b128 v[152:155], v156 offset:2048
	ds_read_b128 v[156:159], v156 offset:3072
	ds_read_b128 v[160:163], v172
	ds_read_b128 v[164:167], v172 offset:1024
	ds_read_b128 v[168:171], v172 offset:2048
	ds_read_b128 v[172:175], v172 offset:3072
	v_lshl_add_u64 v[188:189], s[6:7], 0, v[140:141]
	s_add_i32 m0, s75, 0xc000
	ds_read_b128 v[176:179], v193
	ds_read_b128 v[180:183], v193 offset:1024
	ds_read_b128 v[184:187], v193 offset:2048
	ds_read_b128 v[194:197], v193 offset:3072
	ds_read_b128 v[198:201], v193 offset:4096
	ds_read_b128 v[204:207], v193 offset:5120
	ds_read_b128 v[214:217], v193 offset:6144
	ds_read_b128 v[218:221], v193 offset:7168
	global_load_lds_dwordx4 v[188:189], off
	v_lshl_add_u64 v[188:189], s[6:7], 0, v[138:139]
	s_add_i32 m0, s75, 0xe000
	s_nop 0
	global_load_lds_dwordx4 v[188:189], off
	s_waitcnt vmcnt(8)
	s_waitcnt lgkmcnt(0)
	s_barrier
	s_setprio 1
	s_waitcnt lgkmcnt(0)
	v_mfma_f32_16x16x32_bf16 v[126:129], v[144:147], v[176:179], v[126:129]
	v_mfma_f32_16x16x32_bf16 v[122:125], v[152:155], v[176:179], v[122:125]
	v_mfma_f32_16x16x32_bf16 v[110:113], v[144:147], v[184:187], v[110:113]
	v_mfma_f32_16x16x32_bf16 v[106:109], v[152:155], v[184:187], v[106:109]
	v_mfma_f32_16x16x32_bf16 v[94:97], v[144:147], v[198:201], v[94:97]
	v_mfma_f32_16x16x32_bf16 v[90:93], v[152:155], v[198:201], v[90:93]
	v_mfma_f32_16x16x32_bf16 v[78:81], v[144:147], v[214:217], v[78:81]
	v_mfma_f32_16x16x32_bf16 v[74:77], v[152:155], v[214:217], v[74:77]
	v_mfma_f32_16x16x32_bf16 v[126:129], v[148:151], v[180:183], v[126:129]
	v_mfma_f32_16x16x32_bf16 v[122:125], v[156:159], v[180:183], v[122:125]
	v_mfma_f32_16x16x32_bf16 v[110:113], v[148:151], v[194:197], v[110:113]
	v_mfma_f32_16x16x32_bf16 v[106:109], v[156:159], v[194:197], v[106:109]
	v_mfma_f32_16x16x32_bf16 v[94:97], v[148:151], v[204:207], v[94:97]
	v_mfma_f32_16x16x32_bf16 v[90:93], v[156:159], v[204:207], v[90:93]
	v_mfma_f32_16x16x32_bf16 v[78:81], v[148:151], v[218:221], v[78:81]
	v_mfma_f32_16x16x32_bf16 v[74:77], v[156:159], v[218:221], v[74:77]
	s_setprio 0
	s_setprio 1
	v_mfma_f32_16x16x32_bf16 v[118:121], v[160:163], v[176:179], v[118:121]
	v_mfma_f32_16x16x32_bf16 v[114:117], v[168:171], v[176:179], v[114:117]
	v_mfma_f32_16x16x32_bf16 v[102:105], v[160:163], v[184:187], v[102:105]
	v_mfma_f32_16x16x32_bf16 v[98:101], v[168:171], v[184:187], v[98:101]
	v_mfma_f32_16x16x32_bf16 v[86:89], v[160:163], v[198:201], v[86:89]
	v_mfma_f32_16x16x32_bf16 v[82:85], v[168:171], v[198:201], v[82:85]
	v_mfma_f32_16x16x32_bf16 v[70:73], v[160:163], v[214:217], v[70:73]
	v_mfma_f32_16x16x32_bf16 v[66:69], v[168:171], v[214:217], v[66:69]
	v_mfma_f32_16x16x32_bf16 v[118:121], v[164:167], v[180:183], v[118:121]
	v_mfma_f32_16x16x32_bf16 v[114:117], v[172:175], v[180:183], v[114:117]
	v_mfma_f32_16x16x32_bf16 v[102:105], v[164:167], v[194:197], v[102:105]
	v_mfma_f32_16x16x32_bf16 v[98:101], v[172:175], v[194:197], v[98:101]
	v_mfma_f32_16x16x32_bf16 v[86:89], v[164:167], v[204:207], v[86:89]
	v_mfma_f32_16x16x32_bf16 v[82:85], v[172:175], v[204:207], v[82:85]
	v_mfma_f32_16x16x32_bf16 v[70:73], v[164:167], v[218:221], v[70:73]
	v_mfma_f32_16x16x32_bf16 v[66:69], v[172:175], v[218:221], v[66:69]
	s_setprio 0
	s_barrier
	s_add_i32 s17, s17, s74
	v_lshl_add_u64 v[188:189], s[18:19], 0, v[132:133]
	s_mov_b32 m0, s17
	ds_read_b128 v[176:179], v193 offset:16384
	ds_read_b128 v[180:183], v193 offset:17408
	ds_read_b128 v[184:187], v193 offset:18432
	ds_read_b128 v[194:197], v193 offset:19456
	ds_read_b128 v[198:201], v193 offset:20480
	ds_read_b128 v[204:207], v193 offset:21504
	ds_read_b128 v[214:217], v193 offset:22528
	ds_read_b128 v[218:221], v193 offset:23552
	global_load_lds_dwordx4 v[188:189], off
	s_add_i32 m0, s17, 0x2000
	v_lshl_add_u64 v[222:223], s[18:19], 0, v[136:137]
	s_add_u32 s18, s18, s56
	s_addc_u32 s19, s19, 0
	s_add_i32 s11, s11, s74
	global_load_lds_dwordx4 v[222:223], off
	v_lshl_add_u64 v[224:225], s[18:19], 0, v[132:133]
	s_mov_b32 m0, s11
	v_lshl_add_u64 v[226:227], s[18:19], 0, v[136:137]
	global_load_lds_dwordx4 v[224:225], off
	s_add_i32 m0, s11, 0x2000
	v_lshl_add_u64 v[228:229], s[8:9], 0, v[130:131]
	global_load_lds_dwordx4 v[226:227], off
	s_mov_b32 m0, s75
	v_lshl_add_u64 v[230:231], s[8:9], 0, v[134:135]
	global_load_lds_dwordx4 v[228:229], off
	s_mov_b32 m0, s60
	s_nop 0
	global_load_lds_dwordx4 v[230:231], off
	s_waitcnt vmcnt(8)
	s_waitcnt lgkmcnt(0)
	s_barrier
	s_setprio 1
	s_waitcnt lgkmcnt(0)
	v_mfma_f32_16x16x32_bf16 v[62:65], v[144:147], v[176:179], v[62:65]
	v_mfma_f32_16x16x32_bf16 v[58:61], v[152:155], v[176:179], v[58:61]
	v_mfma_f32_16x16x32_bf16 v[46:49], v[144:147], v[184:187], v[46:49]
	v_mfma_f32_16x16x32_bf16 v[42:45], v[152:155], v[184:187], v[42:45]
	v_mfma_f32_16x16x32_bf16 v[30:33], v[144:147], v[198:201], v[30:33]
	v_mfma_f32_16x16x32_bf16 v[26:29], v[152:155], v[198:201], v[26:29]
	v_mfma_f32_16x16x32_bf16 v[14:17], v[144:147], v[214:217], v[14:17]
	v_mfma_f32_16x16x32_bf16 v[10:13], v[152:155], v[214:217], v[10:13]
	v_mfma_f32_16x16x32_bf16 v[62:65], v[148:151], v[180:183], v[62:65]
	v_mfma_f32_16x16x32_bf16 v[58:61], v[156:159], v[180:183], v[58:61]
	v_mfma_f32_16x16x32_bf16 v[46:49], v[148:151], v[194:197], v[46:49]
	v_mfma_f32_16x16x32_bf16 v[42:45], v[156:159], v[194:197], v[42:45]
	v_mfma_f32_16x16x32_bf16 v[30:33], v[148:151], v[204:207], v[30:33]
	v_mfma_f32_16x16x32_bf16 v[26:29], v[156:159], v[204:207], v[26:29]
	v_mfma_f32_16x16x32_bf16 v[14:17], v[148:151], v[218:221], v[14:17]
	v_mfma_f32_16x16x32_bf16 v[10:13], v[156:159], v[218:221], v[10:13]
	s_setprio 0
	s_setprio 1
	v_mfma_f32_16x16x32_bf16 v[54:57], v[160:163], v[176:179], v[54:57]
	v_mfma_f32_16x16x32_bf16 v[50:53], v[168:171], v[176:179], v[50:53]
	v_mfma_f32_16x16x32_bf16 v[38:41], v[160:163], v[184:187], v[38:41]
	v_mfma_f32_16x16x32_bf16 v[34:37], v[168:171], v[184:187], v[34:37]
	v_mfma_f32_16x16x32_bf16 v[22:25], v[160:163], v[198:201], v[22:25]
	v_mfma_f32_16x16x32_bf16 v[18:21], v[168:171], v[198:201], v[18:21]
	v_mfma_f32_16x16x32_bf16 v[6:9], v[160:163], v[214:217], v[6:9]
	v_mfma_f32_16x16x32_bf16 v[2:5], v[168:171], v[214:217], v[2:5]
	v_mfma_f32_16x16x32_bf16 v[54:57], v[164:167], v[180:183], v[54:57]
	v_mfma_f32_16x16x32_bf16 v[50:53], v[172:175], v[180:183], v[50:53]
	v_mfma_f32_16x16x32_bf16 v[38:41], v[164:167], v[194:197], v[38:41]
	v_mfma_f32_16x16x32_bf16 v[34:37], v[172:175], v[194:197], v[34:37]
	v_mfma_f32_16x16x32_bf16 v[22:25], v[164:167], v[204:207], v[22:25]
	v_mfma_f32_16x16x32_bf16 v[18:21], v[172:175], v[204:207], v[18:21]
	v_mfma_f32_16x16x32_bf16 v[6:9], v[164:167], v[218:221], v[6:9]
	v_mfma_f32_16x16x32_bf16 v[2:5], v[172:175], v[218:221], v[2:5]
	s_setprio 0
	s_barrier
	s_add_i32 s11, 0, 0x18000
	s_add_i32 s17, 0, 0x1c000
	v_add_u32_e32 v156, s11, v191
	v_add_u32_e32 v172, s17, v191
	ds_read_b128 v[144:147], v156
	ds_read_b128 v[148:151], v156 offset:1024
	ds_read_b128 v[152:155], v156 offset:2048
	ds_read_b128 v[156:159], v156 offset:3072
	ds_read_b128 v[160:163], v172
	ds_read_b128 v[164:167], v172 offset:1024
	ds_read_b128 v[168:171], v172 offset:2048
	ds_read_b128 v[172:175], v172 offset:3072
	s_add_u32 s8, s8, s56
	s_addc_u32 s9, s9, 0
	s_mov_b32 m0, s61
	v_lshl_add_u64 v[232:233], s[8:9], 0, v[130:131]
	ds_read_b128 v[176:179], v193 offset:32768
	ds_read_b128 v[180:183], v193 offset:33792
	ds_read_b128 v[184:187], v193 offset:34816
	ds_read_b128 v[194:197], v193 offset:35840
	ds_read_b128 v[198:201], v193 offset:36864
	ds_read_b128 v[204:207], v193 offset:37888
	ds_read_b128 v[214:217], v193 offset:38912
	ds_read_b128 v[218:221], v193 offset:39936
	global_load_lds_dwordx4 v[232:233], off
	v_lshl_add_u64 v[232:233], s[8:9], 0, v[134:135]
	s_mov_b32 m0, s46
	s_nop 0
	global_load_lds_dwordx4 v[232:233], off
	s_waitcnt vmcnt(8)
	s_waitcnt lgkmcnt(0)
	s_barrier
	s_setprio 1
	s_waitcnt lgkmcnt(0)
	v_mfma_f32_16x16x32_bf16 v[126:129], v[144:147], v[176:179], v[126:129]
	v_mfma_f32_16x16x32_bf16 v[122:125], v[152:155], v[176:179], v[122:125]
	v_mfma_f32_16x16x32_bf16 v[110:113], v[144:147], v[184:187], v[110:113]
	v_mfma_f32_16x16x32_bf16 v[106:109], v[152:155], v[184:187], v[106:109]
	v_mfma_f32_16x16x32_bf16 v[94:97], v[144:147], v[198:201], v[94:97]
	v_mfma_f32_16x16x32_bf16 v[90:93], v[152:155], v[198:201], v[90:93]
	v_mfma_f32_16x16x32_bf16 v[78:81], v[144:147], v[214:217], v[78:81]
	v_mfma_f32_16x16x32_bf16 v[74:77], v[152:155], v[214:217], v[74:77]
	v_mfma_f32_16x16x32_bf16 v[126:129], v[148:151], v[180:183], v[126:129]
	v_mfma_f32_16x16x32_bf16 v[122:125], v[156:159], v[180:183], v[122:125]
	v_mfma_f32_16x16x32_bf16 v[110:113], v[148:151], v[194:197], v[110:113]
	v_mfma_f32_16x16x32_bf16 v[106:109], v[156:159], v[194:197], v[106:109]
	v_mfma_f32_16x16x32_bf16 v[94:97], v[148:151], v[204:207], v[94:97]
	v_mfma_f32_16x16x32_bf16 v[90:93], v[156:159], v[204:207], v[90:93]
	v_mfma_f32_16x16x32_bf16 v[78:81], v[148:151], v[218:221], v[78:81]
	v_mfma_f32_16x16x32_bf16 v[74:77], v[156:159], v[218:221], v[74:77]
	s_setprio 0
	s_setprio 1
	v_mfma_f32_16x16x32_bf16 v[118:121], v[160:163], v[176:179], v[118:121]
	v_mfma_f32_16x16x32_bf16 v[114:117], v[168:171], v[176:179], v[114:117]
	v_mfma_f32_16x16x32_bf16 v[102:105], v[160:163], v[184:187], v[102:105]
	v_mfma_f32_16x16x32_bf16 v[98:101], v[168:171], v[184:187], v[98:101]
	v_mfma_f32_16x16x32_bf16 v[86:89], v[160:163], v[198:201], v[86:89]
	v_mfma_f32_16x16x32_bf16 v[82:85], v[168:171], v[198:201], v[82:85]
	v_mfma_f32_16x16x32_bf16 v[70:73], v[160:163], v[214:217], v[70:73]
	v_mfma_f32_16x16x32_bf16 v[66:69], v[168:171], v[214:217], v[66:69]
	v_mfma_f32_16x16x32_bf16 v[118:121], v[164:167], v[180:183], v[118:121]
	v_mfma_f32_16x16x32_bf16 v[114:117], v[172:175], v[180:183], v[114:117]
	v_mfma_f32_16x16x32_bf16 v[102:105], v[164:167], v[194:197], v[102:105]
	v_mfma_f32_16x16x32_bf16 v[98:101], v[172:175], v[194:197], v[98:101]
	v_mfma_f32_16x16x32_bf16 v[86:89], v[164:167], v[204:207], v[86:89]
	v_mfma_f32_16x16x32_bf16 v[82:85], v[172:175], v[204:207], v[82:85]
	v_mfma_f32_16x16x32_bf16 v[70:73], v[164:167], v[218:221], v[70:73]
	v_mfma_f32_16x16x32_bf16 v[66:69], v[172:175], v[218:221], v[66:69]
	s_setprio 0
	s_barrier
	s_add_i32 s8, s11, s74
	v_lshl_add_u64 v[188:189], v[188:189], 0, s[30:31]
	s_mov_b32 m0, s8
	ds_read_b128 v[176:179], v193 offset:49152
	ds_read_b128 v[180:183], v193 offset:50176
	ds_read_b128 v[184:187], v193 offset:51200
	ds_read_b128 v[194:197], v193 offset:52224
	ds_read_b128 v[198:201], v193 offset:53248
	ds_read_b128 v[204:207], v193 offset:54272
	ds_read_b128 v[214:217], v193 offset:55296
	ds_read_b128 v[218:221], v193 offset:56320
	global_load_lds_dwordx4 v[188:189], off
	v_lshl_add_u64 v[188:189], v[222:223], 0, s[30:31]
	s_add_i32 m0, s8, 0x2000
	s_add_i32 s8, s17, s74
	global_load_lds_dwordx4 v[188:189], off
	v_lshl_add_u64 v[188:189], v[224:225], 0, s[30:31]
	s_mov_b32 m0, s8
	s_nop 0
	global_load_lds_dwordx4 v[188:189], off
	v_lshl_add_u64 v[188:189], v[226:227], 0, s[30:31]
	s_add_i32 m0, s8, 0x2000
	s_nop 0
	global_load_lds_dwordx4 v[188:189], off
	v_lshl_add_u64 v[188:189], v[228:229], 0, s[30:31]
	s_mov_b32 m0, s63
	s_nop 0
	global_load_lds_dwordx4 v[188:189], off
	v_lshl_add_u64 v[188:189], v[230:231], 0, s[30:31]
	s_mov_b32 m0, s44
	s_nop 0
	global_load_lds_dwordx4 v[188:189], off
	s_waitcnt vmcnt(8)
	s_waitcnt lgkmcnt(0)
	s_barrier
	s_setprio 1
	s_waitcnt lgkmcnt(0)
	v_mfma_f32_16x16x32_bf16 v[62:65], v[144:147], v[176:179], v[62:65]
	v_mfma_f32_16x16x32_bf16 v[58:61], v[152:155], v[176:179], v[58:61]
	v_mfma_f32_16x16x32_bf16 v[46:49], v[144:147], v[184:187], v[46:49]
	v_mfma_f32_16x16x32_bf16 v[42:45], v[152:155], v[184:187], v[42:45]
	v_mfma_f32_16x16x32_bf16 v[30:33], v[144:147], v[198:201], v[30:33]
	v_mfma_f32_16x16x32_bf16 v[26:29], v[152:155], v[198:201], v[26:29]
	v_mfma_f32_16x16x32_bf16 v[14:17], v[144:147], v[214:217], v[14:17]
	v_mfma_f32_16x16x32_bf16 v[10:13], v[152:155], v[214:217], v[10:13]
	v_mfma_f32_16x16x32_bf16 v[62:65], v[148:151], v[180:183], v[62:65]
	v_mfma_f32_16x16x32_bf16 v[58:61], v[156:159], v[180:183], v[58:61]
	v_mfma_f32_16x16x32_bf16 v[46:49], v[148:151], v[194:197], v[46:49]
	v_mfma_f32_16x16x32_bf16 v[42:45], v[156:159], v[194:197], v[42:45]
	v_mfma_f32_16x16x32_bf16 v[30:33], v[148:151], v[204:207], v[30:33]
	v_mfma_f32_16x16x32_bf16 v[26:29], v[156:159], v[204:207], v[26:29]
	v_mfma_f32_16x16x32_bf16 v[14:17], v[148:151], v[218:221], v[14:17]
	v_mfma_f32_16x16x32_bf16 v[10:13], v[156:159], v[218:221], v[10:13]
	s_setprio 0
	s_setprio 1
	v_mfma_f32_16x16x32_bf16 v[54:57], v[160:163], v[176:179], v[54:57]
	v_mfma_f32_16x16x32_bf16 v[50:53], v[168:171], v[176:179], v[50:53]
	v_mfma_f32_16x16x32_bf16 v[38:41], v[160:163], v[184:187], v[38:41]
	v_mfma_f32_16x16x32_bf16 v[34:37], v[168:171], v[184:187], v[34:37]
	v_mfma_f32_16x16x32_bf16 v[22:25], v[160:163], v[198:201], v[22:25]
	v_mfma_f32_16x16x32_bf16 v[18:21], v[168:171], v[198:201], v[18:21]
	v_mfma_f32_16x16x32_bf16 v[6:9], v[160:163], v[214:217], v[6:9]
	v_mfma_f32_16x16x32_bf16 v[2:5], v[168:171], v[214:217], v[2:5]
	v_mfma_f32_16x16x32_bf16 v[54:57], v[164:167], v[180:183], v[54:57]
	v_mfma_f32_16x16x32_bf16 v[50:53], v[172:175], v[180:183], v[50:53]
	v_mfma_f32_16x16x32_bf16 v[38:41], v[164:167], v[194:197], v[38:41]
	v_mfma_f32_16x16x32_bf16 v[34:37], v[172:175], v[194:197], v[34:37]
	v_mfma_f32_16x16x32_bf16 v[22:25], v[164:167], v[204:207], v[22:25]
	v_mfma_f32_16x16x32_bf16 v[18:21], v[172:175], v[204:207], v[18:21]
	v_mfma_f32_16x16x32_bf16 v[6:9], v[164:167], v[218:221], v[6:9]
	v_mfma_f32_16x16x32_bf16 v[2:5], v[172:175], v[218:221], v[2:5]
	s_add_u32 s15, s15, 0x100
	s_addc_u32 s16, s16, 0
	s_add_u32 s6, s6, 0x100
	s_addc_u32 s7, s7, 0
	s_cmp_ge_u32 s10, s47
	s_mov_b32 s8, s10
	s_setprio 0
	s_barrier
	s_cbranch_scc0 .LBB0_223
	v_readlane_b32 s6, v243, 45
	v_readlane_b32 s7, v243, 46
	s_and_b64 vcc, exec, s[6:7]
	s_cbranch_vccz .LBB0_226
	s_barrier
